# f32 residual epilogue: waves 4-7 enter ~4 us later (mixes reads and writes chip-wide)
# baseline (speedup 1.0000x reference)
; __device__ __forceinline__ unsigned pk2(float lo, float hi) { return pg8::cvt_pk_bf16(lo, hi); }
;     __device__ __forceinline__ void operator()(const pg8::f32x4 (&acc)[2][2][4][2], const pg8::Unit& u, int wr, int wc, int fr, int fq) const {
;         ArgsP a = a0; asm volatile("" : "+s"(a));
;         unsigned char* ws = a->ws; float* out = a->out; const float* base = mode == 0 ? a->in[0] : (const float*)out;
;         bf16_t* aux = mode == 0 ? (bf16_t*)(ws + WS_X1B) : mode == 1 ? (bf16_t*)(ws + WS_X2B) : nullptr; float* ssq = mode == 0 ? (float*)(ws + WS_SSQ_X1) : (float*)(ws + WS_SSQ_X2);
;         const int rowb = u.pm * 256 + wr * 64 + fr, cb = u.pn * 256 + wc * 32 + 4 * fq;
; #pragma unroll
;         for (int ai = 0; ai < 2; ++ai) {
;             f32x4 pre[4][2][2];
; #pragma unroll
;             for (int m = 0; m < 4; ++m)
; #pragma unroll
;                 for (int bj = 0; bj < 2; ++bj)
; #pragma unroll
;                     for (int n = 0; n < 2; ++n) pre[m][bj][n] = *(const f32x4*)(base + (size_t)(rowb + ai * 128 + m * 16) * 2048 + cb + bj * 128 + n * 16);
; #pragma unroll
;             for (int m = 0; m < 4; ++m) {
;                 const int row = rowb + ai * 128 + m * 16; float s = 0.f;
; #pragma unroll
;                 for (int bj = 0; bj < 2; ++bj)
; #pragma unroll
;                     for (int n = 0; n < 2; ++n) {
;                         const size_t off = (size_t)row * 2048 + cb + bj * 128 + n * 16;
;                         const f32x4 o = pre[m][bj][n] + acc[ai][bj][m][n];
;                         *(f32x4*)(out + off) = o;
;                         if (aux) { s += (o[0] * o[0] + o[1] * o[1]) + (o[2] * o[2] + o[3] * o[3]); u32x2 w; w.x = pk2(o[0], o[1]); w.y = pk2(o[2], o[3]); *(u32x2*)(aux + off) = w; }
;                     }
;                 if (aux) { s += __shfl_xor(s, 16); s += __shfl_xor(s, 32); if (fq == 0) atomicAdd(ssq + row, s); }
;             }
;             asm volatile("" ::: "memory");
;         }
.LBB0_673:
	s_and_b64 vcc, exec, s[22:23]
	s_cbranch_vccnz .Lepi_nosleep
	s_sleep 127

; __global__ void __launch_bounds__(512, 2) mk_fwd(Args a_) {
;     ...
;         if (ph + 1 < ph_hi) { if (ph >= 1000) grid.sync(); else xcd_barrier(xbar); }
;     }
.Lpost_getpc0:
	s_add_u32 s98, s98, (.LBB0_7-.Lpost_getpc0)&4294967295
	s_addc_u32 s99, s99, (.LBB0_7-.Lpost_getpc0)>>32
	s_setpc_b64 s[98:99]
	s_nop 0
	s_nop 0
	s_nop 0
	s_nop 0
	s_nop 0
	s_nop 0
	s_nop 0
	s_nop 0
	s_nop 0
	s_nop 0
	s_nop 0
	s_nop 0
	s_nop 0
	s_nop 0
	s_nop 0
	s_nop 0
	s_nop 0
	s_nop 0
	s_nop 0
	s_nop 0
	s_nop 0
	s_nop 0
	s_nop 0
	s_nop 0
	s_nop 0
	s_nop 0
	s_nop 0
	s_nop 0
	s_nop 0
	s_nop 0
	s_nop 0
	s_nop 0
	s_nop 0
	s_nop 0
	s_nop 0
	s_nop 0
	s_nop 0
	s_nop 0
	s_nop 0
	s_nop 0
	s_nop 0
	s_nop 0
	s_nop 0
	s_nop 0
	s_nop 0
	s_nop 0
	s_nop 0
	s_nop 0
	s_nop 0
	s_nop 0
	s_nop 0
	s_nop 0
	s_nop 0
	s_nop 0
	s_nop 0
	s_nop 0
	s_nop 0
	s_nop 0
	s_nop 0
	s_nop 0
	s_nop 0
	s_nop 0
	s_nop 0
	s_nop 0
	s_nop 0
	s_nop 0
	s_nop 0
	s_nop 0
	s_nop 0
	s_nop 0
	s_nop 0
	s_nop 0
	s_nop 0
	s_nop 0
	s_nop 0
	s_nop 0
	s_nop 0
	s_nop 0
	s_nop 0
	s_nop 0
	s_nop 0
	s_nop 0
	s_nop 0
	s_nop 0
	s_nop 0
	s_nop 0
	s_nop 0
	s_nop 0
	s_nop 0
	s_nop 0
	s_nop 0
	s_nop 0
	s_nop 0
	s_nop 0
	s_nop 0
	s_nop 0
	s_nop 0
	s_nop 0
	s_nop 0
	s_nop 0
	s_nop 0
	s_nop 0
	s_nop 0
	s_nop 0
	s_nop 0
	s_nop 0
	s_nop 0
	s_nop 0
	s_nop 0
	s_nop 0
	s_nop 0
	s_nop 0
	s_nop 0
	s_nop 0
	s_nop 0
	s_nop 0
	s_nop 0
	s_nop 0
	s_nop 0
	s_nop 0
	s_nop 0
	s_nop 0
	s_nop 0
	s_nop 0
	s_nop 0
	s_nop 0
	s_nop 0
	s_nop 0
	s_nop 0
	s_nop 0
	s_nop 0
	s_nop 0
	s_nop 0
	s_nop 0
	s_nop 0
	s_nop 0
	s_nop 0
	s_nop 0
	s_nop 0
	s_nop 0
	s_nop 0
	s_nop 0
	s_nop 0
	s_nop 0
	s_nop 0
	s_nop 0
	s_nop 0
	s_nop 0
	s_nop 0
	s_nop 0
	s_nop 0
	s_nop 0
	s_nop 0
	s_nop 0
	s_nop 0
	s_nop 0
	s_nop 0
	s_nop 0
	s_nop 0
	s_nop 0
	s_nop 0
	s_nop 0
	s_nop 0
	s_nop 0
	s_nop 0
	s_nop 0
	s_nop 0
	s_nop 0
	s_nop 0
	s_nop 0
	s_nop 0
	s_nop 0
	s_nop 0
	s_nop 0
	s_nop 0
	s_nop 0
	s_nop 0
	s_nop 0
	s_nop 0
	s_nop 0
	s_nop 0
	s_nop 0
	s_nop 0
	s_nop 0
	s_nop 0
	s_nop 0
	s_nop 0
	s_nop 0
	s_nop 0
	s_nop 0
	s_nop 0
	s_nop 0
	s_nop 0
	s_nop 0
	s_nop 0
	s_nop 0
	s_nop 0
	s_nop 0
	s_nop 0
	s_nop 0
	s_nop 0
	s_nop 0
	s_nop 0
	s_nop 0
	s_nop 0
	s_nop 0
	s_nop 0
	s_nop 0
	s_nop 0
	s_nop 0
	s_nop 0
	s_nop 0
	s_nop 0
	s_nop 0
	s_nop 0
	s_nop 0
	s_nop 0
	s_nop 0
	s_nop 0
	s_nop 0
	s_nop 0
	s_nop 0
	s_nop 0
	s_nop 0
	s_nop 0
	s_nop 0
	s_nop 0
	s_nop 0
	s_nop 0
	s_nop 0
	s_nop 0
	s_nop 0
	s_nop 0
	s_nop 0
	s_nop 0
	s_nop 0
	s_nop 0
	s_nop 0
	s_nop 0
	s_nop 0
	s_nop 0
	s_nop 0
	s_nop 0
	s_nop 0
	s_nop 0
	s_nop 0
	s_nop 0
	s_nop 0
	s_nop 0
	s_nop 0
	s_nop 0
	s_nop 0
	s_nop 0
	s_nop 0
	s_nop 0
	s_nop 0
	s_nop 0
	s_nop 0
	s_nop 0
	s_nop 0
	s_nop 0
	s_nop 0
	s_nop 0
	s_nop 0
	s_nop 0
	s_nop 0
	s_nop 0
	s_nop 0
	s_nop 0
	s_nop 0
	s_nop 0
	s_nop 0
	s_nop 0
	s_nop 0
	s_nop 0
	s_nop 0
	s_nop 0
	s_nop 0
	s_nop 0
	s_nop 0
	s_nop 0
	s_nop 0
	s_nop 0
	s_nop 0
	s_nop 0
	s_nop 0
	s_nop 0
	s_nop 0
	s_nop 0
	s_nop 0
	s_nop 0
	s_nop 0
	s_nop 0
	s_nop 0
	s_nop 0
	s_nop 0
	s_nop 0
	s_nop 0
	s_nop 0
	s_nop 0
	s_nop 0
	s_nop 0
	s_nop 0
	s_nop 0
	s_nop 0
	s_nop 0
	s_nop 0
	s_nop 0
	s_nop 0
	s_nop 0
	s_nop 0
	s_nop 0
	s_nop 0
	s_nop 0
	s_nop 0
	s_nop 0
	s_nop 0
	s_nop 0
	s_nop 0
	s_nop 0
	s_nop 0
	s_nop 0
	s_nop 0
	s_nop 0
	s_nop 0
	s_nop 0
	s_nop 0
	s_nop 0
	s_nop 0
	s_nop 0
	s_nop 0
	s_nop 0
	s_nop 0
	s_nop 0
	s_nop 0
	s_nop 0
	s_nop 0
	s_nop 0
	s_nop 0
	s_nop 0
	s_nop 0
	s_nop 0
	s_nop 0
	s_nop 0
	s_nop 0
	s_nop 0
	s_nop 0
	s_nop 0
	s_nop 0
	s_nop 0
	s_nop 0
	s_nop 0
	s_nop 0
	s_nop 0
	s_nop 0
	s_nop 0
	s_nop 0
	s_nop 0
	s_nop 0
	s_nop 0
	s_nop 0
	s_nop 0
	s_nop 0
	s_nop 0
	s_nop 0
	s_nop 0
	s_nop 0
	s_nop 0
	s_nop 0
	s_nop 0
	s_nop 0
	s_nop 0
	s_nop 0
	s_nop 0
	s_nop 0
	s_nop 0
	s_nop 0
	s_nop 0
	s_nop 0
	s_nop 0
	s_nop 0
	s_nop 0
	s_nop 0
	s_nop 0
	s_nop 0
	s_nop 0
	s_nop 0
	s_nop 0
	s_nop 0
	s_nop 0
	s_nop 0
	s_nop 0
	s_nop 0
	s_nop 0
	s_nop 0
	s_nop 0
	s_nop 0
	s_nop 0
	s_nop 0
	s_nop 0
	s_nop 0
	s_nop 0
	s_nop 0
	s_nop 0
	s_nop 0
	s_nop 0
	s_nop 0
	s_nop 0
	s_nop 0
	s_nop 0
	s_nop 0
	s_nop 0
	s_nop 0
	s_nop 0
	s_nop 0
	s_nop 0
	s_nop 0
	s_nop 0
	s_nop 0
	s_nop 0
	s_nop 0
	s_nop 0
	s_nop 0
	s_nop 0
	s_nop 0
	s_nop 0
	s_nop 0
	s_nop 0
	s_nop 0
	s_nop 0
	s_nop 0
	s_nop 0
	s_nop 0
	s_nop 0
	s_nop 0
	s_nop 0
	s_nop 0
	s_nop 0
	s_nop 0
	s_nop 0
	s_nop 0
	s_nop 0
	s_nop 0
	s_nop 0
	s_nop 0
	s_nop 0
	s_nop 0
	s_nop 0
	s_nop 0
	s_nop 0
	s_nop 0
	s_nop 0
	s_nop 0
	s_nop 0
	s_nop 0
	s_nop 0
	s_nop 0
	s_nop 0
	s_nop 0
	s_nop 0
	s_nop 0
	s_nop 0
	s_nop 0
	s_nop 0
	s_nop 0
	s_nop 0
	s_nop 0
	s_nop 0
	s_nop 0
	s_nop 0
	s_nop 0
	s_nop 0
	s_nop 0
	s_nop 0
	s_nop 0
	s_nop 0
	s_nop 0
	s_nop 0
	s_nop 0
	s_nop 0
	s_nop 0
	s_nop 0
	s_nop 0
	s_nop 0
	s_nop 0
	s_nop 0
	s_nop 0
	s_nop 0
	s_nop 0
	s_nop 0
	s_nop 0
	s_nop 0
	s_nop 0
	s_nop 0
	s_nop 0
	s_nop 0
.LBB0_1140:
	s_endpgm
